# L2 step loop shifted by 4 bytes so its 8-byte DPP instructions sit on 8-byte boundaries
# baseline (speedup 1.0000x reference)
.LBB0_281:
	s_waitcnt lgkmcnt(0)
	s_waitcnt vmcnt(0)
	v_mov_b64_e32 v[2:3], v[84:85]
	v_mov_b64_e32 v[4:5], v[86:87]
	v_mov_b64_e32 v[6:7], v[88:89]
	v_mov_b64_e32 v[8:9], v[90:91]
	v_mov_b64_e32 v[10:11], v[102:103]
	v_mov_b64_e32 v[12:13], v[104:105]
	v_mov_b64_e32 v[14:15], v[106:107]
	v_mov_b64_e32 v[16:17], v[108:109]
	v_mov_b64_e32 v[192:193], v[34:35]
	v_mov_b64_e32 v[194:195], v[32:33]
	v_mov_b64_e32 v[196:197], v[30:31]
	v_mov_b64_e32 v[198:199], v[28:29]
	v_mov_b64_e32 v[200:201], v[26:27]
	v_mov_b64_e32 v[202:203], v[24:25]
	v_mov_b64_e32 v[204:205], v[22:23]
	v_mov_b64_e32 v[206:207], v[20:21]
	s_nop 0

.Ll2_tail:
	s_add_i32 s11, s11, -1
	v_subrev_u32_e32 v126, 64, v126
	s_cmp_eq_u32 s12, 8
	s_mov_b32 s14, s12
	s_cbranch_scc0 .Ll2_step
	s_nop 0
	s_waitcnt vmcnt(0)
	s_add_i32 s26, s10, s43
	s_ashr_i32 s27, s26, 31
	s_lshl_b64 s[28:29], s[26:27], 10
	v_readlane_b32 s76, v255, 54
	v_readlane_b32 s77, v255, 55
	v_lshrrev_b32_e32 v162, 4, v228
	v_and_b32_e32 v163, 15, v228
	v_lshlrev_b32_e32 v163, 4, v163
	s_add_u32 s76, s76, s28
	s_addc_u32 s77, s77, s29
	v_lshl_add_u32 v162, v162, 10, v163
	v_add_u32_e32 v163, 0x1000, v162
	global_load_dwordx4 v[130:133], v162, s[76:77]
	global_load_dwordx4 v[134:137], v162, s[76:77] offset:256
	global_load_dwordx4 v[138:141], v162, s[76:77] offset:512
	global_load_dwordx4 v[142:145], v162, s[76:77] offset:768
	global_load_dwordx4 v[146:149], v163, s[76:77]
	global_load_dwordx4 v[150:153], v163, s[76:77] offset:256
	global_load_dwordx4 v[154:157], v163, s[76:77] offset:512
	global_load_dwordx4 v[158:161], v163, s[76:77] offset:768
